# seam 0->1 replaced by a counter hand-off on the adaLN modulations (write-through stores, 192 producers); phase 1 starts per workgroup without the grid barrier
# speedup vs baseline: 1.0184x; 1.0090x over previous
.LBB0_51:
	s_mul_hi_i32 s0, s62, 0x2aaaaaab
	s_lshr_b32 s1, s0, 31
	s_ashr_i32 s63, s0, 4
	s_add_i32 s63, s63, s1
	s_mul_i32 s0, s63, 0x60
	s_sub_i32 s0, s62, s0
	v_lshl_or_b32 v168, s0, 6, v161
	v_mad_i64_i32 v[0:1], s[0:1], s63, v167, v[164:165]
	v_ashrrev_i32_e32 v169, 31, v168
	v_lshl_add_u64 v[170:171], v[168:169], 2, v[0:1]
	v_mov_b32_e32 v169, 0
	s_mov_b64 s[14:15], 0
	v_mov_b32_e32 v180, v178
	v_mov_b32_e32 v172, 0
	v_mov_b32_e32 v173, v169
	v_mov_b32_e32 v174, 0
	v_mov_b32_e32 v175, v169
	v_readfirstlane_b32 s0, v170
	v_readfirstlane_b32 s1, v171
	s_nop 1
	v_subrev_u32_e32 v176, s0, v170
	s_nop 3
	global_load_dword v0, v176, s[0:1]
	s_add_u32 s0, s0, 0x6000
	s_addc_u32 s1, s1, 0
	global_load_dword v1, v176, s[0:1]
	s_add_u32 s0, s0, 0x6000
	s_addc_u32 s1, s1, 0
	global_load_dword v2, v176, s[0:1]
	s_add_u32 s0, s0, 0x6000
	s_addc_u32 s1, s1, 0
	global_load_dword v3, v176, s[0:1]
	s_add_u32 s0, s0, 0x6000
	s_addc_u32 s1, s1, 0
	global_load_dword v4, v176, s[0:1]
	s_add_u32 s0, s0, 0x6000
	s_addc_u32 s1, s1, 0
	global_load_dword v5, v176, s[0:1]
	s_add_u32 s0, s0, 0x6000
	s_addc_u32 s1, s1, 0
	global_load_dword v6, v176, s[0:1]
	s_add_u32 s0, s0, 0x6000
	s_addc_u32 s1, s1, 0
	global_load_dword v7, v176, s[0:1]
	s_add_u32 s0, s0, 0x6000
	s_addc_u32 s1, s1, 0
	global_load_dword v8, v176, s[0:1]
	s_add_u32 s0, s0, 0x6000
	s_addc_u32 s1, s1, 0
	global_load_dword v9, v176, s[0:1]
	s_add_u32 s0, s0, 0x6000
	s_addc_u32 s1, s1, 0
	global_load_dword v10, v176, s[0:1]
	s_add_u32 s0, s0, 0x6000
	s_addc_u32 s1, s1, 0
	global_load_dword v11, v176, s[0:1]
	s_add_u32 s0, s0, 0x6000
	s_addc_u32 s1, s1, 0
	global_load_dword v12, v176, s[0:1]
	s_add_u32 s0, s0, 0x6000
	s_addc_u32 s1, s1, 0
	global_load_dword v13, v176, s[0:1]
	s_add_u32 s0, s0, 0x6000
	s_addc_u32 s1, s1, 0
	global_load_dword v14, v176, s[0:1]
	s_add_u32 s0, s0, 0x6000
	s_addc_u32 s1, s1, 0
	global_load_dword v15, v176, s[0:1]
	s_add_u32 s0, s0, 0x6000
	s_addc_u32 s1, s1, 0
	global_load_dword v16, v176, s[0:1]
	s_add_u32 s0, s0, 0x6000
	s_addc_u32 s1, s1, 0
	global_load_dword v17, v176, s[0:1]
	s_add_u32 s0, s0, 0x6000
	s_addc_u32 s1, s1, 0
	global_load_dword v18, v176, s[0:1]
	s_add_u32 s0, s0, 0x6000
	s_addc_u32 s1, s1, 0
	global_load_dword v19, v176, s[0:1]
	s_add_u32 s0, s0, 0x6000
	s_addc_u32 s1, s1, 0
	global_load_dword v20, v176, s[0:1]
	s_add_u32 s0, s0, 0x6000
	s_addc_u32 s1, s1, 0
	global_load_dword v21, v176, s[0:1]
	s_add_u32 s0, s0, 0x6000
	s_addc_u32 s1, s1, 0
	global_load_dword v22, v176, s[0:1]
	s_add_u32 s0, s0, 0x6000
	s_addc_u32 s1, s1, 0
	global_load_dword v23, v176, s[0:1]
	s_add_u32 s0, s0, 0x6000
	s_addc_u32 s1, s1, 0
	global_load_dword v24, v176, s[0:1]
	s_add_u32 s0, s0, 0x6000
	s_addc_u32 s1, s1, 0
	global_load_dword v25, v176, s[0:1]
	s_add_u32 s0, s0, 0x6000
	s_addc_u32 s1, s1, 0
	global_load_dword v26, v176, s[0:1]
	s_add_u32 s0, s0, 0x6000
	s_addc_u32 s1, s1, 0
	global_load_dword v27, v176, s[0:1]
	s_add_u32 s0, s0, 0x6000
	s_addc_u32 s1, s1, 0
	global_load_dword v28, v176, s[0:1]
	s_add_u32 s0, s0, 0x6000
	s_addc_u32 s1, s1, 0
	global_load_dword v29, v176, s[0:1]
	s_add_u32 s0, s0, 0x6000
	s_addc_u32 s1, s1, 0
	global_load_dword v30, v176, s[0:1]
	s_add_u32 s0, s0, 0x6000
	s_addc_u32 s1, s1, 0
	global_load_dword v31, v176, s[0:1]
	s_add_u32 s0, s0, 0x6000
	s_addc_u32 s1, s1, 0
	global_load_dword v32, v176, s[0:1]
	s_add_u32 s0, s0, 0x6000
	s_addc_u32 s1, s1, 0
	global_load_dword v33, v176, s[0:1]
	s_add_u32 s0, s0, 0x6000
	s_addc_u32 s1, s1, 0
	global_load_dword v34, v176, s[0:1]
	s_add_u32 s0, s0, 0x6000
	s_addc_u32 s1, s1, 0
	global_load_dword v35, v176, s[0:1]
	s_add_u32 s0, s0, 0x6000
	s_addc_u32 s1, s1, 0
	global_load_dword v36, v176, s[0:1]
	s_add_u32 s0, s0, 0x6000
	s_addc_u32 s1, s1, 0
	global_load_dword v37, v176, s[0:1]
	s_add_u32 s0, s0, 0x6000
	s_addc_u32 s1, s1, 0
	global_load_dword v38, v176, s[0:1]
	s_add_u32 s0, s0, 0x6000
	s_addc_u32 s1, s1, 0
	global_load_dword v39, v176, s[0:1]
	s_add_u32 s0, s0, 0x6000
	s_addc_u32 s1, s1, 0
	global_load_dword v40, v176, s[0:1]
	s_add_u32 s0, s0, 0x6000
	s_addc_u32 s1, s1, 0
	global_load_dword v41, v176, s[0:1]
	s_add_u32 s0, s0, 0x6000
	s_addc_u32 s1, s1, 0
	global_load_dword v42, v176, s[0:1]
	s_add_u32 s0, s0, 0x6000
	s_addc_u32 s1, s1, 0
	global_load_dword v43, v176, s[0:1]
	s_add_u32 s0, s0, 0x6000
	s_addc_u32 s1, s1, 0
	global_load_dword v44, v176, s[0:1]
	s_add_u32 s0, s0, 0x6000
	s_addc_u32 s1, s1, 0
	global_load_dword v45, v176, s[0:1]
	s_add_u32 s0, s0, 0x6000
	s_addc_u32 s1, s1, 0
	global_load_dword v46, v176, s[0:1]
	s_add_u32 s0, s0, 0x6000
	s_addc_u32 s1, s1, 0
	global_load_dword v47, v176, s[0:1]
	s_add_u32 s0, s0, 0x6000
	s_addc_u32 s1, s1, 0
	ds_read_b128 v[64:67], v180
	ds_read_b128 v[68:71], v180 offset:16
	ds_read_b128 v[72:75], v180 offset:32
	ds_read_b128 v[76:79], v180 offset:48
	ds_read_b128 v[80:83], v180 offset:4096
	ds_read_b128 v[84:87], v180 offset:4112
	ds_read_b128 v[88:91], v180 offset:4128
	ds_read_b128 v[92:95], v180 offset:4144
	ds_read_b128 v[96:99], v180 offset:8192
	ds_read_b128 v[100:103], v180 offset:8208
	ds_read_b128 v[104:107], v180 offset:8224
	ds_read_b128 v[108:111], v180 offset:8240
	ds_read_b128 v[112:115], v180 offset:12288
	ds_read_b128 v[116:119], v180 offset:12304
	ds_read_b128 v[120:123], v180 offset:12320
	ds_read_b128 v[124:127], v180 offset:12336
	ds_read_b128 v[128:131], v180 offset:16384
	ds_read_b128 v[132:135], v180 offset:16400
	ds_read_b128 v[136:139], v180 offset:16416
	ds_read_b128 v[140:143], v180 offset:16432
	s_waitcnt vmcnt(32)
	global_load_dword v48, v176, s[0:1]
	s_add_u32 s0, s0, 0x6000
	s_addc_u32 s1, s1, 0
	global_load_dword v49, v176, s[0:1]
	s_add_u32 s0, s0, 0x6000
	s_addc_u32 s1, s1, 0
	global_load_dword v50, v176, s[0:1]
	s_add_u32 s0, s0, 0x6000
	s_addc_u32 s1, s1, 0
	global_load_dword v51, v176, s[0:1]
	s_add_u32 s0, s0, 0x6000
	s_addc_u32 s1, s1, 0
	global_load_dword v52, v176, s[0:1]
	s_add_u32 s0, s0, 0x6000
	s_addc_u32 s1, s1, 0
	global_load_dword v53, v176, s[0:1]
	s_add_u32 s0, s0, 0x6000
	s_addc_u32 s1, s1, 0
	global_load_dword v54, v176, s[0:1]
	s_add_u32 s0, s0, 0x6000
	s_addc_u32 s1, s1, 0
	global_load_dword v55, v176, s[0:1]
	s_add_u32 s0, s0, 0x6000
	s_addc_u32 s1, s1, 0
	global_load_dword v56, v176, s[0:1]
	s_add_u32 s0, s0, 0x6000
	s_addc_u32 s1, s1, 0
	global_load_dword v57, v176, s[0:1]
	s_add_u32 s0, s0, 0x6000
	s_addc_u32 s1, s1, 0
	global_load_dword v58, v176, s[0:1]
	s_add_u32 s0, s0, 0x6000
	s_addc_u32 s1, s1, 0
	global_load_dword v59, v176, s[0:1]
	s_add_u32 s0, s0, 0x6000
	s_addc_u32 s1, s1, 0
	global_load_dword v60, v176, s[0:1]
	s_add_u32 s0, s0, 0x6000
	s_addc_u32 s1, s1, 0
	global_load_dword v61, v176, s[0:1]
	s_add_u32 s0, s0, 0x6000
	s_addc_u32 s1, s1, 0
	global_load_dword v62, v176, s[0:1]
	s_add_u32 s0, s0, 0x6000
	s_addc_u32 s1, s1, 0
	global_load_dword v63, v176, s[0:1]
	s_add_u32 s0, s0, 0x6000
	s_addc_u32 s1, s1, 0
	s_waitcnt lgkmcnt(0)
	v_fmac_f32_e32 v172, v0, v64
	v_fmac_f32_e32 v173, v0, v80
	v_fmac_f32_e32 v174, v0, v96
	v_fmac_f32_e32 v175, v0, v112
	v_fmac_f32_e32 v169, v0, v128
	v_fmac_f32_e32 v172, v1, v65
	v_fmac_f32_e32 v173, v1, v81
	v_fmac_f32_e32 v174, v1, v97
	v_fmac_f32_e32 v175, v1, v113
	v_fmac_f32_e32 v169, v1, v129
	v_fmac_f32_e32 v172, v2, v66
	v_fmac_f32_e32 v173, v2, v82
	v_fmac_f32_e32 v174, v2, v98
	v_fmac_f32_e32 v175, v2, v114
	v_fmac_f32_e32 v169, v2, v130
	v_fmac_f32_e32 v172, v3, v67
	v_fmac_f32_e32 v173, v3, v83
	v_fmac_f32_e32 v174, v3, v99
	v_fmac_f32_e32 v175, v3, v115
	v_fmac_f32_e32 v169, v3, v131
	v_fmac_f32_e32 v172, v4, v68
	v_fmac_f32_e32 v173, v4, v84
	v_fmac_f32_e32 v174, v4, v100
	v_fmac_f32_e32 v175, v4, v116
	v_fmac_f32_e32 v169, v4, v132
	v_fmac_f32_e32 v172, v5, v69
	v_fmac_f32_e32 v173, v5, v85
	v_fmac_f32_e32 v174, v5, v101
	v_fmac_f32_e32 v175, v5, v117
	v_fmac_f32_e32 v169, v5, v133
	v_fmac_f32_e32 v172, v6, v70
	v_fmac_f32_e32 v173, v6, v86
	v_fmac_f32_e32 v174, v6, v102
	v_fmac_f32_e32 v175, v6, v118
	v_fmac_f32_e32 v169, v6, v134
	v_fmac_f32_e32 v172, v7, v71
	v_fmac_f32_e32 v173, v7, v87
	v_fmac_f32_e32 v174, v7, v103
	v_fmac_f32_e32 v175, v7, v119
	v_fmac_f32_e32 v169, v7, v135
	v_fmac_f32_e32 v172, v8, v72
	v_fmac_f32_e32 v173, v8, v88
	v_fmac_f32_e32 v174, v8, v104
	v_fmac_f32_e32 v175, v8, v120
	v_fmac_f32_e32 v169, v8, v136
	v_fmac_f32_e32 v172, v9, v73
	v_fmac_f32_e32 v173, v9, v89
	v_fmac_f32_e32 v174, v9, v105
	v_fmac_f32_e32 v175, v9, v121
	v_fmac_f32_e32 v169, v9, v137
	v_fmac_f32_e32 v172, v10, v74
	v_fmac_f32_e32 v173, v10, v90
	v_fmac_f32_e32 v174, v10, v106
	v_fmac_f32_e32 v175, v10, v122
	v_fmac_f32_e32 v169, v10, v138
	v_fmac_f32_e32 v172, v11, v75
	v_fmac_f32_e32 v173, v11, v91
	v_fmac_f32_e32 v174, v11, v107
	v_fmac_f32_e32 v175, v11, v123
	v_fmac_f32_e32 v169, v11, v139
	v_fmac_f32_e32 v172, v12, v76
	v_fmac_f32_e32 v173, v12, v92
	v_fmac_f32_e32 v174, v12, v108
	v_fmac_f32_e32 v175, v12, v124
	v_fmac_f32_e32 v169, v12, v140
	v_fmac_f32_e32 v172, v13, v77
	v_fmac_f32_e32 v173, v13, v93
	v_fmac_f32_e32 v174, v13, v109
	v_fmac_f32_e32 v175, v13, v125
	v_fmac_f32_e32 v169, v13, v141
	v_fmac_f32_e32 v172, v14, v78
	v_fmac_f32_e32 v173, v14, v94
	v_fmac_f32_e32 v174, v14, v110
	v_fmac_f32_e32 v175, v14, v126
	v_fmac_f32_e32 v169, v14, v142
	v_fmac_f32_e32 v172, v15, v79
	v_fmac_f32_e32 v173, v15, v95
	v_fmac_f32_e32 v174, v15, v111
	v_fmac_f32_e32 v175, v15, v127
	v_fmac_f32_e32 v169, v15, v143
	ds_read_b128 v[64:67], v180 offset:64
	ds_read_b128 v[68:71], v180 offset:80
	ds_read_b128 v[72:75], v180 offset:96
	ds_read_b128 v[76:79], v180 offset:112
	ds_read_b128 v[80:83], v180 offset:4160
	ds_read_b128 v[84:87], v180 offset:4176
	ds_read_b128 v[88:91], v180 offset:4192
	ds_read_b128 v[92:95], v180 offset:4208
	ds_read_b128 v[96:99], v180 offset:8256
	ds_read_b128 v[100:103], v180 offset:8272
	ds_read_b128 v[104:107], v180 offset:8288
	ds_read_b128 v[108:111], v180 offset:8304
	ds_read_b128 v[112:115], v180 offset:12352
	ds_read_b128 v[116:119], v180 offset:12368
	ds_read_b128 v[120:123], v180 offset:12384
	ds_read_b128 v[124:127], v180 offset:12400
	ds_read_b128 v[128:131], v180 offset:16448
	ds_read_b128 v[132:135], v180 offset:16464
	ds_read_b128 v[136:139], v180 offset:16480
	ds_read_b128 v[140:143], v180 offset:16496
	s_waitcnt vmcnt(32)
	global_load_dword v0, v176, s[0:1]
	s_add_u32 s0, s0, 0x6000
	s_addc_u32 s1, s1, 0
	global_load_dword v1, v176, s[0:1]
	s_add_u32 s0, s0, 0x6000
	s_addc_u32 s1, s1, 0
	global_load_dword v2, v176, s[0:1]
	s_add_u32 s0, s0, 0x6000
	s_addc_u32 s1, s1, 0
	global_load_dword v3, v176, s[0:1]
	s_add_u32 s0, s0, 0x6000
	s_addc_u32 s1, s1, 0
	global_load_dword v4, v176, s[0:1]
	s_add_u32 s0, s0, 0x6000
	s_addc_u32 s1, s1, 0
	global_load_dword v5, v176, s[0:1]
	s_add_u32 s0, s0, 0x6000
	s_addc_u32 s1, s1, 0
	global_load_dword v6, v176, s[0:1]
	s_add_u32 s0, s0, 0x6000
	s_addc_u32 s1, s1, 0
	global_load_dword v7, v176, s[0:1]
	s_add_u32 s0, s0, 0x6000
	s_addc_u32 s1, s1, 0
	global_load_dword v8, v176, s[0:1]
	s_add_u32 s0, s0, 0x6000
	s_addc_u32 s1, s1, 0
	global_load_dword v9, v176, s[0:1]
	s_add_u32 s0, s0, 0x6000
	s_addc_u32 s1, s1, 0
	global_load_dword v10, v176, s[0:1]
	s_add_u32 s0, s0, 0x6000
	s_addc_u32 s1, s1, 0
	global_load_dword v11, v176, s[0:1]
	s_add_u32 s0, s0, 0x6000
	s_addc_u32 s1, s1, 0
	global_load_dword v12, v176, s[0:1]
	s_add_u32 s0, s0, 0x6000
	s_addc_u32 s1, s1, 0
	global_load_dword v13, v176, s[0:1]
	s_add_u32 s0, s0, 0x6000
	s_addc_u32 s1, s1, 0
	global_load_dword v14, v176, s[0:1]
	s_add_u32 s0, s0, 0x6000
	s_addc_u32 s1, s1, 0
	global_load_dword v15, v176, s[0:1]
	s_add_u32 s0, s0, 0x6000
	s_addc_u32 s1, s1, 0
	s_waitcnt lgkmcnt(0)
	v_fmac_f32_e32 v172, v16, v64
	v_fmac_f32_e32 v173, v16, v80
	v_fmac_f32_e32 v174, v16, v96
	v_fmac_f32_e32 v175, v16, v112
	v_fmac_f32_e32 v169, v16, v128
	v_fmac_f32_e32 v172, v17, v65
	v_fmac_f32_e32 v173, v17, v81
	v_fmac_f32_e32 v174, v17, v97
	v_fmac_f32_e32 v175, v17, v113
	v_fmac_f32_e32 v169, v17, v129
	v_fmac_f32_e32 v172, v18, v66
	v_fmac_f32_e32 v173, v18, v82
	v_fmac_f32_e32 v174, v18, v98
	v_fmac_f32_e32 v175, v18, v114
	v_fmac_f32_e32 v169, v18, v130
	v_fmac_f32_e32 v172, v19, v67
	v_fmac_f32_e32 v173, v19, v83
	v_fmac_f32_e32 v174, v19, v99
	v_fmac_f32_e32 v175, v19, v115
	v_fmac_f32_e32 v169, v19, v131
	v_fmac_f32_e32 v172, v20, v68
	v_fmac_f32_e32 v173, v20, v84
	v_fmac_f32_e32 v174, v20, v100
	v_fmac_f32_e32 v175, v20, v116
	v_fmac_f32_e32 v169, v20, v132
	v_fmac_f32_e32 v172, v21, v69
	v_fmac_f32_e32 v173, v21, v85
	v_fmac_f32_e32 v174, v21, v101
	v_fmac_f32_e32 v175, v21, v117
	v_fmac_f32_e32 v169, v21, v133
	v_fmac_f32_e32 v172, v22, v70
	v_fmac_f32_e32 v173, v22, v86
	v_fmac_f32_e32 v174, v22, v102
	v_fmac_f32_e32 v175, v22, v118
	v_fmac_f32_e32 v169, v22, v134
	v_fmac_f32_e32 v172, v23, v71
	v_fmac_f32_e32 v173, v23, v87
	v_fmac_f32_e32 v174, v23, v103
	v_fmac_f32_e32 v175, v23, v119
	v_fmac_f32_e32 v169, v23, v135
	v_fmac_f32_e32 v172, v24, v72
	v_fmac_f32_e32 v173, v24, v88
	v_fmac_f32_e32 v174, v24, v104
	v_fmac_f32_e32 v175, v24, v120
	v_fmac_f32_e32 v169, v24, v136
	v_fmac_f32_e32 v172, v25, v73
	v_fmac_f32_e32 v173, v25, v89
	v_fmac_f32_e32 v174, v25, v105
	v_fmac_f32_e32 v175, v25, v121
	v_fmac_f32_e32 v169, v25, v137
	v_fmac_f32_e32 v172, v26, v74
	v_fmac_f32_e32 v173, v26, v90
	v_fmac_f32_e32 v174, v26, v106
	v_fmac_f32_e32 v175, v26, v122
	v_fmac_f32_e32 v169, v26, v138
	v_fmac_f32_e32 v172, v27, v75
	v_fmac_f32_e32 v173, v27, v91
	v_fmac_f32_e32 v174, v27, v107
	v_fmac_f32_e32 v175, v27, v123
	v_fmac_f32_e32 v169, v27, v139
	v_fmac_f32_e32 v172, v28, v76
	v_fmac_f32_e32 v173, v28, v92
	v_fmac_f32_e32 v174, v28, v108
	v_fmac_f32_e32 v175, v28, v124
	v_fmac_f32_e32 v169, v28, v140
	v_fmac_f32_e32 v172, v29, v77
	v_fmac_f32_e32 v173, v29, v93
	v_fmac_f32_e32 v174, v29, v109
	v_fmac_f32_e32 v175, v29, v125
	v_fmac_f32_e32 v169, v29, v141
	v_fmac_f32_e32 v172, v30, v78
	v_fmac_f32_e32 v173, v30, v94
	v_fmac_f32_e32 v174, v30, v110
	v_fmac_f32_e32 v175, v30, v126
	v_fmac_f32_e32 v169, v30, v142
	v_fmac_f32_e32 v172, v31, v79
	v_fmac_f32_e32 v173, v31, v95
	v_fmac_f32_e32 v174, v31, v111
	v_fmac_f32_e32 v175, v31, v127
	v_fmac_f32_e32 v169, v31, v143
	ds_read_b128 v[64:67], v180 offset:128
	ds_read_b128 v[68:71], v180 offset:144
	ds_read_b128 v[72:75], v180 offset:160
	ds_read_b128 v[76:79], v180 offset:176
	ds_read_b128 v[80:83], v180 offset:4224
	ds_read_b128 v[84:87], v180 offset:4240
	ds_read_b128 v[88:91], v180 offset:4256
	ds_read_b128 v[92:95], v180 offset:4272
	ds_read_b128 v[96:99], v180 offset:8320
	ds_read_b128 v[100:103], v180 offset:8336
	ds_read_b128 v[104:107], v180 offset:8352
	ds_read_b128 v[108:111], v180 offset:8368
	ds_read_b128 v[112:115], v180 offset:12416
	ds_read_b128 v[116:119], v180 offset:12432
	ds_read_b128 v[120:123], v180 offset:12448
	ds_read_b128 v[124:127], v180 offset:12464
	ds_read_b128 v[128:131], v180 offset:16512
	ds_read_b128 v[132:135], v180 offset:16528
	ds_read_b128 v[136:139], v180 offset:16544
	ds_read_b128 v[140:143], v180 offset:16560
	s_waitcnt vmcnt(32)
	global_load_dword v16, v176, s[0:1]
	s_add_u32 s0, s0, 0x6000
	s_addc_u32 s1, s1, 0
	global_load_dword v17, v176, s[0:1]
	s_add_u32 s0, s0, 0x6000
	s_addc_u32 s1, s1, 0
	global_load_dword v18, v176, s[0:1]
	s_add_u32 s0, s0, 0x6000
	s_addc_u32 s1, s1, 0
	global_load_dword v19, v176, s[0:1]
	s_add_u32 s0, s0, 0x6000
	s_addc_u32 s1, s1, 0
	global_load_dword v20, v176, s[0:1]
	s_add_u32 s0, s0, 0x6000
	s_addc_u32 s1, s1, 0
	global_load_dword v21, v176, s[0:1]
	s_add_u32 s0, s0, 0x6000
	s_addc_u32 s1, s1, 0
	global_load_dword v22, v176, s[0:1]
	s_add_u32 s0, s0, 0x6000
	s_addc_u32 s1, s1, 0
	global_load_dword v23, v176, s[0:1]
	s_add_u32 s0, s0, 0x6000
	s_addc_u32 s1, s1, 0
	global_load_dword v24, v176, s[0:1]
	s_add_u32 s0, s0, 0x6000
	s_addc_u32 s1, s1, 0
	global_load_dword v25, v176, s[0:1]
	s_add_u32 s0, s0, 0x6000
	s_addc_u32 s1, s1, 0
	global_load_dword v26, v176, s[0:1]
	s_add_u32 s0, s0, 0x6000
	s_addc_u32 s1, s1, 0
	global_load_dword v27, v176, s[0:1]
	s_add_u32 s0, s0, 0x6000
	s_addc_u32 s1, s1, 0
	global_load_dword v28, v176, s[0:1]
	s_add_u32 s0, s0, 0x6000
	s_addc_u32 s1, s1, 0
	global_load_dword v29, v176, s[0:1]
	s_add_u32 s0, s0, 0x6000
	s_addc_u32 s1, s1, 0
	global_load_dword v30, v176, s[0:1]
	s_add_u32 s0, s0, 0x6000
	s_addc_u32 s1, s1, 0
	global_load_dword v31, v176, s[0:1]
	s_add_u32 s0, s0, 0x6000
	s_addc_u32 s1, s1, 0
	s_waitcnt lgkmcnt(0)
	v_fmac_f32_e32 v172, v32, v64
	v_fmac_f32_e32 v173, v32, v80
	v_fmac_f32_e32 v174, v32, v96
	v_fmac_f32_e32 v175, v32, v112
	v_fmac_f32_e32 v169, v32, v128
	v_fmac_f32_e32 v172, v33, v65
	v_fmac_f32_e32 v173, v33, v81
	v_fmac_f32_e32 v174, v33, v97
	v_fmac_f32_e32 v175, v33, v113
	v_fmac_f32_e32 v169, v33, v129
	v_fmac_f32_e32 v172, v34, v66
	v_fmac_f32_e32 v173, v34, v82
	v_fmac_f32_e32 v174, v34, v98
	v_fmac_f32_e32 v175, v34, v114
	v_fmac_f32_e32 v169, v34, v130
	v_fmac_f32_e32 v172, v35, v67
	v_fmac_f32_e32 v173, v35, v83
	v_fmac_f32_e32 v174, v35, v99
	v_fmac_f32_e32 v175, v35, v115
	v_fmac_f32_e32 v169, v35, v131
	v_fmac_f32_e32 v172, v36, v68
	v_fmac_f32_e32 v173, v36, v84
	v_fmac_f32_e32 v174, v36, v100
	v_fmac_f32_e32 v175, v36, v116
	v_fmac_f32_e32 v169, v36, v132
	v_fmac_f32_e32 v172, v37, v69
	v_fmac_f32_e32 v173, v37, v85
	v_fmac_f32_e32 v174, v37, v101
	v_fmac_f32_e32 v175, v37, v117
	v_fmac_f32_e32 v169, v37, v133
	v_fmac_f32_e32 v172, v38, v70
	v_fmac_f32_e32 v173, v38, v86
	v_fmac_f32_e32 v174, v38, v102
	v_fmac_f32_e32 v175, v38, v118
	v_fmac_f32_e32 v169, v38, v134
	v_fmac_f32_e32 v172, v39, v71
	v_fmac_f32_e32 v173, v39, v87
	v_fmac_f32_e32 v174, v39, v103
	v_fmac_f32_e32 v175, v39, v119
	v_fmac_f32_e32 v169, v39, v135
	v_fmac_f32_e32 v172, v40, v72
	v_fmac_f32_e32 v173, v40, v88
	v_fmac_f32_e32 v174, v40, v104
	v_fmac_f32_e32 v175, v40, v120
	v_fmac_f32_e32 v169, v40, v136
	v_fmac_f32_e32 v172, v41, v73
	v_fmac_f32_e32 v173, v41, v89
	v_fmac_f32_e32 v174, v41, v105
	v_fmac_f32_e32 v175, v41, v121
	v_fmac_f32_e32 v169, v41, v137
	v_fmac_f32_e32 v172, v42, v74
	v_fmac_f32_e32 v173, v42, v90
	v_fmac_f32_e32 v174, v42, v106
	v_fmac_f32_e32 v175, v42, v122
	v_fmac_f32_e32 v169, v42, v138
	v_fmac_f32_e32 v172, v43, v75
	v_fmac_f32_e32 v173, v43, v91
	v_fmac_f32_e32 v174, v43, v107
	v_fmac_f32_e32 v175, v43, v123
	v_fmac_f32_e32 v169, v43, v139
	v_fmac_f32_e32 v172, v44, v76
	v_fmac_f32_e32 v173, v44, v92
	v_fmac_f32_e32 v174, v44, v108
	v_fmac_f32_e32 v175, v44, v124
	v_fmac_f32_e32 v169, v44, v140
	v_fmac_f32_e32 v172, v45, v77
	v_fmac_f32_e32 v173, v45, v93
	v_fmac_f32_e32 v174, v45, v109
	v_fmac_f32_e32 v175, v45, v125
	v_fmac_f32_e32 v169, v45, v141
	v_fmac_f32_e32 v172, v46, v78
	v_fmac_f32_e32 v173, v46, v94
	v_fmac_f32_e32 v174, v46, v110
	v_fmac_f32_e32 v175, v46, v126
	v_fmac_f32_e32 v169, v46, v142
	v_fmac_f32_e32 v172, v47, v79
	v_fmac_f32_e32 v173, v47, v95
	v_fmac_f32_e32 v174, v47, v111
	v_fmac_f32_e32 v175, v47, v127
	v_fmac_f32_e32 v169, v47, v143
	ds_read_b128 v[64:67], v180 offset:192
	ds_read_b128 v[68:71], v180 offset:208
	ds_read_b128 v[72:75], v180 offset:224
	ds_read_b128 v[76:79], v180 offset:240
	ds_read_b128 v[80:83], v180 offset:4288
	ds_read_b128 v[84:87], v180 offset:4304
	ds_read_b128 v[88:91], v180 offset:4320
	ds_read_b128 v[92:95], v180 offset:4336
	ds_read_b128 v[96:99], v180 offset:8384
	ds_read_b128 v[100:103], v180 offset:8400
	ds_read_b128 v[104:107], v180 offset:8416
	ds_read_b128 v[108:111], v180 offset:8432
	ds_read_b128 v[112:115], v180 offset:12480
	ds_read_b128 v[116:119], v180 offset:12496
	ds_read_b128 v[120:123], v180 offset:12512
	ds_read_b128 v[124:127], v180 offset:12528
	ds_read_b128 v[128:131], v180 offset:16576
	ds_read_b128 v[132:135], v180 offset:16592
	ds_read_b128 v[136:139], v180 offset:16608
	ds_read_b128 v[140:143], v180 offset:16624
	s_waitcnt vmcnt(32)
	global_load_dword v32, v176, s[0:1]
	s_add_u32 s0, s0, 0x6000
	s_addc_u32 s1, s1, 0
	global_load_dword v33, v176, s[0:1]
	s_add_u32 s0, s0, 0x6000
	s_addc_u32 s1, s1, 0
	global_load_dword v34, v176, s[0:1]
	s_add_u32 s0, s0, 0x6000
	s_addc_u32 s1, s1, 0
	global_load_dword v35, v176, s[0:1]
	s_add_u32 s0, s0, 0x6000
	s_addc_u32 s1, s1, 0
	global_load_dword v36, v176, s[0:1]
	s_add_u32 s0, s0, 0x6000
	s_addc_u32 s1, s1, 0
	global_load_dword v37, v176, s[0:1]
	s_add_u32 s0, s0, 0x6000
	s_addc_u32 s1, s1, 0
	global_load_dword v38, v176, s[0:1]
	s_add_u32 s0, s0, 0x6000
	s_addc_u32 s1, s1, 0
	global_load_dword v39, v176, s[0:1]
	s_add_u32 s0, s0, 0x6000
	s_addc_u32 s1, s1, 0
	global_load_dword v40, v176, s[0:1]
	s_add_u32 s0, s0, 0x6000
	s_addc_u32 s1, s1, 0
	global_load_dword v41, v176, s[0:1]
	s_add_u32 s0, s0, 0x6000
	s_addc_u32 s1, s1, 0
	global_load_dword v42, v176, s[0:1]
	s_add_u32 s0, s0, 0x6000
	s_addc_u32 s1, s1, 0
	global_load_dword v43, v176, s[0:1]
	s_add_u32 s0, s0, 0x6000
	s_addc_u32 s1, s1, 0
	global_load_dword v44, v176, s[0:1]
	s_add_u32 s0, s0, 0x6000
	s_addc_u32 s1, s1, 0
	global_load_dword v45, v176, s[0:1]
	s_add_u32 s0, s0, 0x6000
	s_addc_u32 s1, s1, 0
	global_load_dword v46, v176, s[0:1]
	s_add_u32 s0, s0, 0x6000
	s_addc_u32 s1, s1, 0
	global_load_dword v47, v176, s[0:1]
	s_add_u32 s0, s0, 0x6000
	s_addc_u32 s1, s1, 0
	s_waitcnt lgkmcnt(0)
	v_fmac_f32_e32 v172, v48, v64
	v_fmac_f32_e32 v173, v48, v80
	v_fmac_f32_e32 v174, v48, v96
	v_fmac_f32_e32 v175, v48, v112
	v_fmac_f32_e32 v169, v48, v128
	v_fmac_f32_e32 v172, v49, v65
	v_fmac_f32_e32 v173, v49, v81
	v_fmac_f32_e32 v174, v49, v97
	v_fmac_f32_e32 v175, v49, v113
	v_fmac_f32_e32 v169, v49, v129
	v_fmac_f32_e32 v172, v50, v66
	v_fmac_f32_e32 v173, v50, v82
	v_fmac_f32_e32 v174, v50, v98
	v_fmac_f32_e32 v175, v50, v114
	v_fmac_f32_e32 v169, v50, v130
	v_fmac_f32_e32 v172, v51, v67
	v_fmac_f32_e32 v173, v51, v83
	v_fmac_f32_e32 v174, v51, v99
	v_fmac_f32_e32 v175, v51, v115
	v_fmac_f32_e32 v169, v51, v131
	v_fmac_f32_e32 v172, v52, v68
	v_fmac_f32_e32 v173, v52, v84
	v_fmac_f32_e32 v174, v52, v100
	v_fmac_f32_e32 v175, v52, v116
	v_fmac_f32_e32 v169, v52, v132
	v_fmac_f32_e32 v172, v53, v69
	v_fmac_f32_e32 v173, v53, v85
	v_fmac_f32_e32 v174, v53, v101
	v_fmac_f32_e32 v175, v53, v117
	v_fmac_f32_e32 v169, v53, v133
	v_fmac_f32_e32 v172, v54, v70
	v_fmac_f32_e32 v173, v54, v86
	v_fmac_f32_e32 v174, v54, v102
	v_fmac_f32_e32 v175, v54, v118
	v_fmac_f32_e32 v169, v54, v134
	v_fmac_f32_e32 v172, v55, v71
	v_fmac_f32_e32 v173, v55, v87
	v_fmac_f32_e32 v174, v55, v103
	v_fmac_f32_e32 v175, v55, v119
	v_fmac_f32_e32 v169, v55, v135
	v_fmac_f32_e32 v172, v56, v72
	v_fmac_f32_e32 v173, v56, v88
	v_fmac_f32_e32 v174, v56, v104
	v_fmac_f32_e32 v175, v56, v120
	v_fmac_f32_e32 v169, v56, v136
	v_fmac_f32_e32 v172, v57, v73
	v_fmac_f32_e32 v173, v57, v89
	v_fmac_f32_e32 v174, v57, v105
	v_fmac_f32_e32 v175, v57, v121
	v_fmac_f32_e32 v169, v57, v137
	v_fmac_f32_e32 v172, v58, v74
	v_fmac_f32_e32 v173, v58, v90
	v_fmac_f32_e32 v174, v58, v106
	v_fmac_f32_e32 v175, v58, v122
	v_fmac_f32_e32 v169, v58, v138
	v_fmac_f32_e32 v172, v59, v75
	v_fmac_f32_e32 v173, v59, v91
	v_fmac_f32_e32 v174, v59, v107
	v_fmac_f32_e32 v175, v59, v123
	v_fmac_f32_e32 v169, v59, v139
	v_fmac_f32_e32 v172, v60, v76
	v_fmac_f32_e32 v173, v60, v92
	v_fmac_f32_e32 v174, v60, v108
	v_fmac_f32_e32 v175, v60, v124
	v_fmac_f32_e32 v169, v60, v140
	v_fmac_f32_e32 v172, v61, v77
	v_fmac_f32_e32 v173, v61, v93
	v_fmac_f32_e32 v174, v61, v109
	v_fmac_f32_e32 v175, v61, v125
	v_fmac_f32_e32 v169, v61, v141
	v_fmac_f32_e32 v172, v62, v78
	v_fmac_f32_e32 v173, v62, v94
	v_fmac_f32_e32 v174, v62, v110
	v_fmac_f32_e32 v175, v62, v126
	v_fmac_f32_e32 v169, v62, v142
	v_fmac_f32_e32 v172, v63, v79
	v_fmac_f32_e32 v173, v63, v95
	v_fmac_f32_e32 v174, v63, v111
	v_fmac_f32_e32 v175, v63, v127
	v_fmac_f32_e32 v169, v63, v143
	ds_read_b128 v[64:67], v180 offset:256
	ds_read_b128 v[68:71], v180 offset:272
	ds_read_b128 v[72:75], v180 offset:288
	ds_read_b128 v[76:79], v180 offset:304
	ds_read_b128 v[80:83], v180 offset:4352
	ds_read_b128 v[84:87], v180 offset:4368
	ds_read_b128 v[88:91], v180 offset:4384
	ds_read_b128 v[92:95], v180 offset:4400
	ds_read_b128 v[96:99], v180 offset:8448
	ds_read_b128 v[100:103], v180 offset:8464
	ds_read_b128 v[104:107], v180 offset:8480
	ds_read_b128 v[108:111], v180 offset:8496
	ds_read_b128 v[112:115], v180 offset:12544
	ds_read_b128 v[116:119], v180 offset:12560
	ds_read_b128 v[120:123], v180 offset:12576
	ds_read_b128 v[124:127], v180 offset:12592
	ds_read_b128 v[128:131], v180 offset:16640
	ds_read_b128 v[132:135], v180 offset:16656
	ds_read_b128 v[136:139], v180 offset:16672
	ds_read_b128 v[140:143], v180 offset:16688
	s_waitcnt vmcnt(32)
	global_load_dword v48, v176, s[0:1]
	s_add_u32 s0, s0, 0x6000
	s_addc_u32 s1, s1, 0
	global_load_dword v49, v176, s[0:1]
	s_add_u32 s0, s0, 0x6000
	s_addc_u32 s1, s1, 0
	global_load_dword v50, v176, s[0:1]
	s_add_u32 s0, s0, 0x6000
	s_addc_u32 s1, s1, 0
	global_load_dword v51, v176, s[0:1]
	s_add_u32 s0, s0, 0x6000
	s_addc_u32 s1, s1, 0
	global_load_dword v52, v176, s[0:1]
	s_add_u32 s0, s0, 0x6000
	s_addc_u32 s1, s1, 0
	global_load_dword v53, v176, s[0:1]
	s_add_u32 s0, s0, 0x6000
	s_addc_u32 s1, s1, 0
	global_load_dword v54, v176, s[0:1]
	s_add_u32 s0, s0, 0x6000
	s_addc_u32 s1, s1, 0
	global_load_dword v55, v176, s[0:1]
	s_add_u32 s0, s0, 0x6000
	s_addc_u32 s1, s1, 0
	global_load_dword v56, v176, s[0:1]
	s_add_u32 s0, s0, 0x6000
	s_addc_u32 s1, s1, 0
	global_load_dword v57, v176, s[0:1]
	s_add_u32 s0, s0, 0x6000
	s_addc_u32 s1, s1, 0
	global_load_dword v58, v176, s[0:1]
	s_add_u32 s0, s0, 0x6000
	s_addc_u32 s1, s1, 0
	global_load_dword v59, v176, s[0:1]
	s_add_u32 s0, s0, 0x6000
	s_addc_u32 s1, s1, 0
	global_load_dword v60, v176, s[0:1]
	s_add_u32 s0, s0, 0x6000
	s_addc_u32 s1, s1, 0
	global_load_dword v61, v176, s[0:1]
	s_add_u32 s0, s0, 0x6000
	s_addc_u32 s1, s1, 0
	global_load_dword v62, v176, s[0:1]
	s_add_u32 s0, s0, 0x6000
	s_addc_u32 s1, s1, 0
	global_load_dword v63, v176, s[0:1]
	s_add_u32 s0, s0, 0x6000
	s_addc_u32 s1, s1, 0
	s_waitcnt lgkmcnt(0)
	v_fmac_f32_e32 v172, v0, v64
	v_fmac_f32_e32 v173, v0, v80
	v_fmac_f32_e32 v174, v0, v96
	v_fmac_f32_e32 v175, v0, v112
	v_fmac_f32_e32 v169, v0, v128
	v_fmac_f32_e32 v172, v1, v65
	v_fmac_f32_e32 v173, v1, v81
	v_fmac_f32_e32 v174, v1, v97
	v_fmac_f32_e32 v175, v1, v113
	v_fmac_f32_e32 v169, v1, v129
	v_fmac_f32_e32 v172, v2, v66
	v_fmac_f32_e32 v173, v2, v82
	v_fmac_f32_e32 v174, v2, v98
	v_fmac_f32_e32 v175, v2, v114
	v_fmac_f32_e32 v169, v2, v130
	v_fmac_f32_e32 v172, v3, v67
	v_fmac_f32_e32 v173, v3, v83
	v_fmac_f32_e32 v174, v3, v99
	v_fmac_f32_e32 v175, v3, v115
	v_fmac_f32_e32 v169, v3, v131
	v_fmac_f32_e32 v172, v4, v68
	v_fmac_f32_e32 v173, v4, v84
	v_fmac_f32_e32 v174, v4, v100
	v_fmac_f32_e32 v175, v4, v116
	v_fmac_f32_e32 v169, v4, v132
	v_fmac_f32_e32 v172, v5, v69
	v_fmac_f32_e32 v173, v5, v85
	v_fmac_f32_e32 v174, v5, v101
	v_fmac_f32_e32 v175, v5, v117
	v_fmac_f32_e32 v169, v5, v133
	v_fmac_f32_e32 v172, v6, v70
	v_fmac_f32_e32 v173, v6, v86
	v_fmac_f32_e32 v174, v6, v102
	v_fmac_f32_e32 v175, v6, v118
	v_fmac_f32_e32 v169, v6, v134
	v_fmac_f32_e32 v172, v7, v71
	v_fmac_f32_e32 v173, v7, v87
	v_fmac_f32_e32 v174, v7, v103
	v_fmac_f32_e32 v175, v7, v119
	v_fmac_f32_e32 v169, v7, v135
	v_fmac_f32_e32 v172, v8, v72
	v_fmac_f32_e32 v173, v8, v88
	v_fmac_f32_e32 v174, v8, v104
	v_fmac_f32_e32 v175, v8, v120
	v_fmac_f32_e32 v169, v8, v136
	v_fmac_f32_e32 v172, v9, v73
	v_fmac_f32_e32 v173, v9, v89
	v_fmac_f32_e32 v174, v9, v105
	v_fmac_f32_e32 v175, v9, v121
	v_fmac_f32_e32 v169, v9, v137
	v_fmac_f32_e32 v172, v10, v74
	v_fmac_f32_e32 v173, v10, v90
	v_fmac_f32_e32 v174, v10, v106
	v_fmac_f32_e32 v175, v10, v122
	v_fmac_f32_e32 v169, v10, v138
	v_fmac_f32_e32 v172, v11, v75
	v_fmac_f32_e32 v173, v11, v91
	v_fmac_f32_e32 v174, v11, v107
	v_fmac_f32_e32 v175, v11, v123
	v_fmac_f32_e32 v169, v11, v139
	v_fmac_f32_e32 v172, v12, v76
	v_fmac_f32_e32 v173, v12, v92
	v_fmac_f32_e32 v174, v12, v108
	v_fmac_f32_e32 v175, v12, v124
	v_fmac_f32_e32 v169, v12, v140
	v_fmac_f32_e32 v172, v13, v77
	v_fmac_f32_e32 v173, v13, v93
	v_fmac_f32_e32 v174, v13, v109
	v_fmac_f32_e32 v175, v13, v125
	v_fmac_f32_e32 v169, v13, v141
	v_fmac_f32_e32 v172, v14, v78
	v_fmac_f32_e32 v173, v14, v94
	v_fmac_f32_e32 v174, v14, v110
	v_fmac_f32_e32 v175, v14, v126
	v_fmac_f32_e32 v169, v14, v142
	v_fmac_f32_e32 v172, v15, v79
	v_fmac_f32_e32 v173, v15, v95
	v_fmac_f32_e32 v174, v15, v111
	v_fmac_f32_e32 v175, v15, v127
	v_fmac_f32_e32 v169, v15, v143
	ds_read_b128 v[64:67], v180 offset:320
	ds_read_b128 v[68:71], v180 offset:336
	ds_read_b128 v[72:75], v180 offset:352
	ds_read_b128 v[76:79], v180 offset:368
	ds_read_b128 v[80:83], v180 offset:4416
	ds_read_b128 v[84:87], v180 offset:4432
	ds_read_b128 v[88:91], v180 offset:4448
	ds_read_b128 v[92:95], v180 offset:4464
	ds_read_b128 v[96:99], v180 offset:8512
	ds_read_b128 v[100:103], v180 offset:8528
	ds_read_b128 v[104:107], v180 offset:8544
	ds_read_b128 v[108:111], v180 offset:8560
	ds_read_b128 v[112:115], v180 offset:12608
	ds_read_b128 v[116:119], v180 offset:12624
	ds_read_b128 v[120:123], v180 offset:12640
	ds_read_b128 v[124:127], v180 offset:12656
	ds_read_b128 v[128:131], v180 offset:16704
	ds_read_b128 v[132:135], v180 offset:16720
	ds_read_b128 v[136:139], v180 offset:16736
	ds_read_b128 v[140:143], v180 offset:16752
	s_waitcnt vmcnt(32)
	s_waitcnt lgkmcnt(0)
	v_fmac_f32_e32 v172, v16, v64
	v_fmac_f32_e32 v173, v16, v80
	v_fmac_f32_e32 v174, v16, v96
	v_fmac_f32_e32 v175, v16, v112
	v_fmac_f32_e32 v169, v16, v128
	v_fmac_f32_e32 v172, v17, v65
	v_fmac_f32_e32 v173, v17, v81
	v_fmac_f32_e32 v174, v17, v97
	v_fmac_f32_e32 v175, v17, v113
	v_fmac_f32_e32 v169, v17, v129
	v_fmac_f32_e32 v172, v18, v66
	v_fmac_f32_e32 v173, v18, v82
	v_fmac_f32_e32 v174, v18, v98
	v_fmac_f32_e32 v175, v18, v114
	v_fmac_f32_e32 v169, v18, v130
	v_fmac_f32_e32 v172, v19, v67
	v_fmac_f32_e32 v173, v19, v83
	v_fmac_f32_e32 v174, v19, v99
	v_fmac_f32_e32 v175, v19, v115
	v_fmac_f32_e32 v169, v19, v131
	v_fmac_f32_e32 v172, v20, v68
	v_fmac_f32_e32 v173, v20, v84
	v_fmac_f32_e32 v174, v20, v100
	v_fmac_f32_e32 v175, v20, v116
	v_fmac_f32_e32 v169, v20, v132
	v_fmac_f32_e32 v172, v21, v69
	v_fmac_f32_e32 v173, v21, v85
	v_fmac_f32_e32 v174, v21, v101
	v_fmac_f32_e32 v175, v21, v117
	v_fmac_f32_e32 v169, v21, v133
	v_fmac_f32_e32 v172, v22, v70
	v_fmac_f32_e32 v173, v22, v86
	v_fmac_f32_e32 v174, v22, v102
	v_fmac_f32_e32 v175, v22, v118
	v_fmac_f32_e32 v169, v22, v134
	v_fmac_f32_e32 v172, v23, v71
	v_fmac_f32_e32 v173, v23, v87
	v_fmac_f32_e32 v174, v23, v103
	v_fmac_f32_e32 v175, v23, v119
	v_fmac_f32_e32 v169, v23, v135
	v_fmac_f32_e32 v172, v24, v72
	v_fmac_f32_e32 v173, v24, v88
	v_fmac_f32_e32 v174, v24, v104
	v_fmac_f32_e32 v175, v24, v120
	v_fmac_f32_e32 v169, v24, v136
	v_fmac_f32_e32 v172, v25, v73
	v_fmac_f32_e32 v173, v25, v89
	v_fmac_f32_e32 v174, v25, v105
	v_fmac_f32_e32 v175, v25, v121
	v_fmac_f32_e32 v169, v25, v137
	v_fmac_f32_e32 v172, v26, v74
	v_fmac_f32_e32 v173, v26, v90
	v_fmac_f32_e32 v174, v26, v106
	v_fmac_f32_e32 v175, v26, v122
	v_fmac_f32_e32 v169, v26, v138
	v_fmac_f32_e32 v172, v27, v75
	v_fmac_f32_e32 v173, v27, v91
	v_fmac_f32_e32 v174, v27, v107
	v_fmac_f32_e32 v175, v27, v123
	v_fmac_f32_e32 v169, v27, v139
	v_fmac_f32_e32 v172, v28, v76
	v_fmac_f32_e32 v173, v28, v92
	v_fmac_f32_e32 v174, v28, v108
	v_fmac_f32_e32 v175, v28, v124
	v_fmac_f32_e32 v169, v28, v140
	v_fmac_f32_e32 v172, v29, v77
	v_fmac_f32_e32 v173, v29, v93
	v_fmac_f32_e32 v174, v29, v109
	v_fmac_f32_e32 v175, v29, v125
	v_fmac_f32_e32 v169, v29, v141
	v_fmac_f32_e32 v172, v30, v78
	v_fmac_f32_e32 v173, v30, v94
	v_fmac_f32_e32 v174, v30, v110
	v_fmac_f32_e32 v175, v30, v126
	v_fmac_f32_e32 v169, v30, v142
	v_fmac_f32_e32 v172, v31, v79
	v_fmac_f32_e32 v173, v31, v95
	v_fmac_f32_e32 v174, v31, v111
	v_fmac_f32_e32 v175, v31, v127
	v_fmac_f32_e32 v169, v31, v143
	ds_read_b128 v[64:67], v180 offset:384
	ds_read_b128 v[68:71], v180 offset:400
	ds_read_b128 v[72:75], v180 offset:416
	ds_read_b128 v[76:79], v180 offset:432
	ds_read_b128 v[80:83], v180 offset:4480
	ds_read_b128 v[84:87], v180 offset:4496
	ds_read_b128 v[88:91], v180 offset:4512
	ds_read_b128 v[92:95], v180 offset:4528
	ds_read_b128 v[96:99], v180 offset:8576
	ds_read_b128 v[100:103], v180 offset:8592
	ds_read_b128 v[104:107], v180 offset:8608
	ds_read_b128 v[108:111], v180 offset:8624
	ds_read_b128 v[112:115], v180 offset:12672
	ds_read_b128 v[116:119], v180 offset:12688
	ds_read_b128 v[120:123], v180 offset:12704
	ds_read_b128 v[124:127], v180 offset:12720
	ds_read_b128 v[128:131], v180 offset:16768
	ds_read_b128 v[132:135], v180 offset:16784
	ds_read_b128 v[136:139], v180 offset:16800
	ds_read_b128 v[140:143], v180 offset:16816
	s_waitcnt vmcnt(16)
	s_waitcnt lgkmcnt(0)
	v_fmac_f32_e32 v172, v32, v64
	v_fmac_f32_e32 v173, v32, v80
	v_fmac_f32_e32 v174, v32, v96
	v_fmac_f32_e32 v175, v32, v112
	v_fmac_f32_e32 v169, v32, v128
	v_fmac_f32_e32 v172, v33, v65
	v_fmac_f32_e32 v173, v33, v81
	v_fmac_f32_e32 v174, v33, v97
	v_fmac_f32_e32 v175, v33, v113
	v_fmac_f32_e32 v169, v33, v129
	v_fmac_f32_e32 v172, v34, v66
	v_fmac_f32_e32 v173, v34, v82
	v_fmac_f32_e32 v174, v34, v98
	v_fmac_f32_e32 v175, v34, v114
	v_fmac_f32_e32 v169, v34, v130
	v_fmac_f32_e32 v172, v35, v67
	v_fmac_f32_e32 v173, v35, v83
	v_fmac_f32_e32 v174, v35, v99
	v_fmac_f32_e32 v175, v35, v115
	v_fmac_f32_e32 v169, v35, v131
	v_fmac_f32_e32 v172, v36, v68
	v_fmac_f32_e32 v173, v36, v84
	v_fmac_f32_e32 v174, v36, v100
	v_fmac_f32_e32 v175, v36, v116
	v_fmac_f32_e32 v169, v36, v132
	v_fmac_f32_e32 v172, v37, v69
	v_fmac_f32_e32 v173, v37, v85
	v_fmac_f32_e32 v174, v37, v101
	v_fmac_f32_e32 v175, v37, v117
	v_fmac_f32_e32 v169, v37, v133
	v_fmac_f32_e32 v172, v38, v70
	v_fmac_f32_e32 v173, v38, v86
	v_fmac_f32_e32 v174, v38, v102
	v_fmac_f32_e32 v175, v38, v118
	v_fmac_f32_e32 v169, v38, v134
	v_fmac_f32_e32 v172, v39, v71
	v_fmac_f32_e32 v173, v39, v87
	v_fmac_f32_e32 v174, v39, v103
	v_fmac_f32_e32 v175, v39, v119
	v_fmac_f32_e32 v169, v39, v135
	v_fmac_f32_e32 v172, v40, v72
	v_fmac_f32_e32 v173, v40, v88
	v_fmac_f32_e32 v174, v40, v104
	v_fmac_f32_e32 v175, v40, v120
	v_fmac_f32_e32 v169, v40, v136
	v_fmac_f32_e32 v172, v41, v73
	v_fmac_f32_e32 v173, v41, v89
	v_fmac_f32_e32 v174, v41, v105
	v_fmac_f32_e32 v175, v41, v121
	v_fmac_f32_e32 v169, v41, v137
	v_fmac_f32_e32 v172, v42, v74
	v_fmac_f32_e32 v173, v42, v90
	v_fmac_f32_e32 v174, v42, v106
	v_fmac_f32_e32 v175, v42, v122
	v_fmac_f32_e32 v169, v42, v138
	v_fmac_f32_e32 v172, v43, v75
	v_fmac_f32_e32 v173, v43, v91
	v_fmac_f32_e32 v174, v43, v107
	v_fmac_f32_e32 v175, v43, v123
	v_fmac_f32_e32 v169, v43, v139
	v_fmac_f32_e32 v172, v44, v76
	v_fmac_f32_e32 v173, v44, v92
	v_fmac_f32_e32 v174, v44, v108
	v_fmac_f32_e32 v175, v44, v124
	v_fmac_f32_e32 v169, v44, v140
	v_fmac_f32_e32 v172, v45, v77
	v_fmac_f32_e32 v173, v45, v93
	v_fmac_f32_e32 v174, v45, v109
	v_fmac_f32_e32 v175, v45, v125
	v_fmac_f32_e32 v169, v45, v141
	v_fmac_f32_e32 v172, v46, v78
	v_fmac_f32_e32 v173, v46, v94
	v_fmac_f32_e32 v174, v46, v110
	v_fmac_f32_e32 v175, v46, v126
	v_fmac_f32_e32 v169, v46, v142
	v_fmac_f32_e32 v172, v47, v79
	v_fmac_f32_e32 v173, v47, v95
	v_fmac_f32_e32 v174, v47, v111
	v_fmac_f32_e32 v175, v47, v127
	v_fmac_f32_e32 v169, v47, v143
	ds_read_b128 v[64:67], v180 offset:448
	ds_read_b128 v[68:71], v180 offset:464
	ds_read_b128 v[72:75], v180 offset:480
	ds_read_b128 v[76:79], v180 offset:496
	ds_read_b128 v[80:83], v180 offset:4544
	ds_read_b128 v[84:87], v180 offset:4560
	ds_read_b128 v[88:91], v180 offset:4576
	ds_read_b128 v[92:95], v180 offset:4592
	ds_read_b128 v[96:99], v180 offset:8640
	ds_read_b128 v[100:103], v180 offset:8656
	ds_read_b128 v[104:107], v180 offset:8672
	ds_read_b128 v[108:111], v180 offset:8688
	ds_read_b128 v[112:115], v180 offset:12736
	ds_read_b128 v[116:119], v180 offset:12752
	ds_read_b128 v[120:123], v180 offset:12768
	ds_read_b128 v[124:127], v180 offset:12784
	ds_read_b128 v[128:131], v180 offset:16832
	ds_read_b128 v[132:135], v180 offset:16848
	ds_read_b128 v[136:139], v180 offset:16864
	ds_read_b128 v[140:143], v180 offset:16880
	s_waitcnt vmcnt(0)
	s_waitcnt lgkmcnt(0)
	v_fmac_f32_e32 v172, v48, v64
	v_fmac_f32_e32 v173, v48, v80
	v_fmac_f32_e32 v174, v48, v96
	v_fmac_f32_e32 v175, v48, v112
	v_fmac_f32_e32 v169, v48, v128
	v_fmac_f32_e32 v172, v49, v65
	v_fmac_f32_e32 v173, v49, v81
	v_fmac_f32_e32 v174, v49, v97
	v_fmac_f32_e32 v175, v49, v113
	v_fmac_f32_e32 v169, v49, v129
	v_fmac_f32_e32 v172, v50, v66
	v_fmac_f32_e32 v173, v50, v82
	v_fmac_f32_e32 v174, v50, v98
	v_fmac_f32_e32 v175, v50, v114
	v_fmac_f32_e32 v169, v50, v130
	v_fmac_f32_e32 v172, v51, v67
	v_fmac_f32_e32 v173, v51, v83
	v_fmac_f32_e32 v174, v51, v99
	v_fmac_f32_e32 v175, v51, v115
	v_fmac_f32_e32 v169, v51, v131
	v_fmac_f32_e32 v172, v52, v68
	v_fmac_f32_e32 v173, v52, v84
	v_fmac_f32_e32 v174, v52, v100
	v_fmac_f32_e32 v175, v52, v116
	v_fmac_f32_e32 v169, v52, v132
	v_fmac_f32_e32 v172, v53, v69
	v_fmac_f32_e32 v173, v53, v85
	v_fmac_f32_e32 v174, v53, v101
	v_fmac_f32_e32 v175, v53, v117
	v_fmac_f32_e32 v169, v53, v133
	v_fmac_f32_e32 v172, v54, v70
	v_fmac_f32_e32 v173, v54, v86
	v_fmac_f32_e32 v174, v54, v102
	v_fmac_f32_e32 v175, v54, v118
	v_fmac_f32_e32 v169, v54, v134
	v_fmac_f32_e32 v172, v55, v71
	v_fmac_f32_e32 v173, v55, v87
	v_fmac_f32_e32 v174, v55, v103
	v_fmac_f32_e32 v175, v55, v119
	v_fmac_f32_e32 v169, v55, v135
	v_fmac_f32_e32 v172, v56, v72
	v_fmac_f32_e32 v173, v56, v88
	v_fmac_f32_e32 v174, v56, v104
	v_fmac_f32_e32 v175, v56, v120
	v_fmac_f32_e32 v169, v56, v136
	v_fmac_f32_e32 v172, v57, v73
	v_fmac_f32_e32 v173, v57, v89
	v_fmac_f32_e32 v174, v57, v105
	v_fmac_f32_e32 v175, v57, v121
	v_fmac_f32_e32 v169, v57, v137
	v_fmac_f32_e32 v172, v58, v74
	v_fmac_f32_e32 v173, v58, v90
	v_fmac_f32_e32 v174, v58, v106
	v_fmac_f32_e32 v175, v58, v122
	v_fmac_f32_e32 v169, v58, v138
	v_fmac_f32_e32 v172, v59, v75
	v_fmac_f32_e32 v173, v59, v91
	v_fmac_f32_e32 v174, v59, v107
	v_fmac_f32_e32 v175, v59, v123
	v_fmac_f32_e32 v169, v59, v139
	v_fmac_f32_e32 v172, v60, v76
	v_fmac_f32_e32 v173, v60, v92
	v_fmac_f32_e32 v174, v60, v108
	v_fmac_f32_e32 v175, v60, v124
	v_fmac_f32_e32 v169, v60, v140
	v_fmac_f32_e32 v172, v61, v77
	v_fmac_f32_e32 v173, v61, v93
	v_fmac_f32_e32 v174, v61, v109
	v_fmac_f32_e32 v175, v61, v125
	v_fmac_f32_e32 v169, v61, v141
	v_fmac_f32_e32 v172, v62, v78
	v_fmac_f32_e32 v173, v62, v94
	v_fmac_f32_e32 v174, v62, v110
	v_fmac_f32_e32 v175, v62, v126
	v_fmac_f32_e32 v169, v62, v142
	v_fmac_f32_e32 v172, v63, v79
	v_fmac_f32_e32 v173, v63, v95
	v_fmac_f32_e32 v174, v63, v111
	v_fmac_f32_e32 v175, v63, v127
	v_fmac_f32_e32 v169, v63, v143
	ds_write2st64_b32 v166, v172, v173 offset0:128 offset1:129
	ds_write2st64_b32 v166, v174, v175 offset0:130 offset1:131
	ds_write_b32 v166, v169 offset:33792
	s_waitcnt lgkmcnt(0)
	s_barrier
	s_and_saveexec_b64 s[0:1], vcc
	s_cbranch_execz .LBB0_50
	s_mul_i32 s14, s63, 0x1800
	v_add_u32_e32 v0, s14, v168
	v_ashrrev_i32_e32 v1, 31, v0
	v_lshl_add_u64 v[0:1], v[0:1], 2, s[12:13]
	flat_load_dword v10, v[0:1]
	ds_read2st64_b32 v[0:1], v179 offset0:128 offset1:133
	ds_read2st64_b32 v[2:3], v179 offset0:138 offset1:143
	ds_read2st64_b32 v[4:5], v179 offset0:148 offset1:153
	ds_read2st64_b32 v[6:7], v179 offset0:158 offset1:163
	v_mad_u64_u32 v[8:9], s[14:15], s63, 5, v[162:163]
	s_waitcnt lgkmcnt(0)
	v_add_f32_e32 v0, 0, v0
	v_add_f32_e32 v0, v0, v1
	v_add_f32_e32 v0, v0, v2
	v_add_f32_e32 v0, v0, v3
	v_add_f32_e32 v0, v0, v4
	v_add_f32_e32 v0, v0, v5
	v_mad_u64_u32 v[8:9], s[14:15], v8, s49, v[168:169]
	v_add_f32_e32 v0, v0, v6
	v_ashrrev_i32_e32 v9, 31, v8
	v_add_f32_e32 v0, v0, v7
	s_waitcnt vmcnt(0)
	v_add_f32_e32 v2, v0, v10
	v_lshl_add_u64 v[0:1], v[8:9], 2, s[54:55]
	global_store_dword v[0:1], v2, off sc0 sc1
	s_branch .LBB0_50
.Lada_sig:
	s_waitcnt vmcnt(0)
	s_barrier
	s_cmp_lg_u32 s94, 0
	s_cbranch_scc1 .LBB0_55
	s_add_u32 s0, s54, 0xd603f80
	s_addc_u32 s1, s55, 0
	s_mov_b64 exec, 1
	v_mov_b32_e32 v0, 0
	v_mov_b32_e32 v1, 1
	global_atomic_add v0, v1, s[0:1]
	s_mov_b64 exec, -1

.LBB0_71:
	s_cmp_gt_i32 s41, 1
	s_cselect_b64 s[0:1], -1, 0
	s_and_b64 s[4:5], s[0:1], s[4:5]
	s_andn2_b64 vcc, exec, s[4:5]
	s_cbranch_vccnz .LBB0_121
	s_cmpk_lg_i32 s56, 0x100
	s_cbranch_scc1 .Lq01_seam
	s_waitcnt vmcnt(0) lgkmcnt(0)
	s_cmp_lg_u32 s94, 0
	s_cbranch_scc1 .Lq01_wdone
	s_add_u32 s4, s54, 0xd603f80
	s_addc_u32 s5, s55, 0
	v_mov_b32_e32 v0, 0
	s_mov_b32 s9, 0
.Lq01_poll:
	global_load_dword v1, v0, s[4:5] sc1
	s_waitcnt vmcnt(0)
	v_readfirstlane_b32 s10, v1
	s_cmpk_ge_u32 s10, 0xc0
	s_cbranch_scc1 .Lq01_pdone
	s_sleep 1
	s_add_i32 s9, s9, 1
	s_cmp_lt_u32 s9, 0x40000
	s_cbranch_scc1 .Lq01_poll

.Lq01_wdone:
	s_barrier
	s_branch .LBB0_121
.Lq01_seam:
	s_waitcnt vmcnt(0)
	s_barrier
	s_mov_b64 s[4:5], exec
	v_readlane_b32 s10, v246, 0
	v_readlane_b32 s11, v246, 1
	s_and_b64 s[10:11], s[4:5], s[10:11]
	s_mov_b64 exec, s[10:11]
	s_cbranch_execz .LBB0_120
	s_add_i32 s9, 0, 0x20000
	v_mov_b32_e32 v0, s9
	s_waitcnt vmcnt(0) expcnt(0) lgkmcnt(0)
	ds_read_b32 v2, v0
	s_add_i32 s9, 0, 0x20004
	v_mov_b32_e32 v0, s9
	ds_read_b32 v0, v0
	s_waitcnt lgkmcnt(1)
	v_cmp_ne_u32_e32 vcc, 0, v2
	s_cbranch_vccnz .LBB0_88
	s_add_u32 s10, s54, 0xd600200
	s_addc_u32 s11, s55, 0
	s_add_u32 s12, s54, 0xd600400
	s_addc_u32 s13, s55, 0
	s_add_u32 s14, s54, 0xd600500
	s_addc_u32 s15, s55, 0
	s_add_u32 s16, s54, 0xd600600
	s_addc_u32 s17, s55, 0
	s_add_u32 s18, s54, 0xd600700
	s_addc_u32 s19, s55, 0
	s_add_u32 s20, s54, 0xd600800
	s_addc_u32 s21, s55, 0
	s_add_u32 s22, s54, 0xd600900
	s_addc_u32 s23, s55, 0
	s_add_u32 s26, s54, 0xd600a00
	s_addc_u32 s27, s55, 0
	s_add_u32 s28, s54, 0xd600b00
	s_addc_u32 s29, s55, 0
	s_add_u32 s30, s54, 0xd600c00
	s_addc_u32 s31, s55, 0
	s_add_u32 s34, s54, 0xd600d00
	s_addc_u32 s35, s55, 0
	s_add_u32 s36, s54, 0xd600e00
	s_addc_u32 s37, s55, 0
	s_add_u32 s38, s54, 0xd600f00
	s_addc_u32 s39, s55, 0
	s_add_u32 s44, s54, 0xd601000
	s_addc_u32 s45, s55, 0
	s_add_u32 s46, s54, 0xd601100
	s_addc_u32 s47, s55, 0
	s_add_u32 s48, s54, 0xd601200
	v_readlane_b32 s9, v246, 2
	s_addc_u32 s49, s55, 0
	s_mul_i32 s9, s57, s9
	s_add_u32 s62, s54, 0xd601300
	s_mul_i32 s9, s9, s56
	s_addc_u32 s63, s55, 0
	s_mov_b32 s24, 1
	v_mov_b32_e32 v16, 0
	s_branch .LBB0_76
